# v49 + final RMSNorm loop: gain hoisted, four chunk loads per row batched, counted waits; head-norm loop unrolled x2 with next-row prefetch
# speedup vs baseline: 1.0553x; 1.0252x over previous
; DI unsigned pk2(float a, float b) { f32x2 v = {a, b}; hbf2 r = __builtin_convertvector(v, hbf2); return __builtin_bit_cast(unsigned, r); }
; DI float bflo(unsigned u) { return __uint_as_float(u << 16); }
; DI float bfhi(unsigned u) { return __uint_as_float(u & 0xffff0000u); }
; DI int tid_fresh() { int t = threadIdx.x; asm volatile("" : "+v"(t)); return t; }
; DI void headnorm_phase(const Params& p) {
;     const int tid = tid_fresh(), lane = tid & 63, wid = tid >> 6;
;     bf16_t* OG = (bf16_t*)(p.ws + OFF_R3);
;     const float* HSS = (const float*)(p.ws + OFF_HSS);
;     for (int r = blockIdx.x * 8 + wid; r < MR + 16; r += gridDim.x * 8) {
;         const float sc = rsqrtf(HSS[r * 4 + (lane >> 4)] * (1.0f / 256.0f) + EPS);
;         bf16_t* op = OG + (size_t)r * 2048 + lane * 16;
; #pragma unroll
;         for (int i = 0; i < 2; ++i) {
;             const u32x4 v = *(const u32x4*)(op + i * 8);
;             u32x4 w;
;             w.x = pk2(bflo(v.x) * sc, bfhi(v.x) * sc); w.y = pk2(bflo(v.y) * sc, bfhi(v.y) * sc);
;             w.z = pk2(bflo(v.z) * sc, bfhi(v.z) * sc); w.w = pk2(bflo(v.w) * sc, bfhi(v.w) * sc);
;             *(u32x4*)(op + i * 8) = w;
;         }
;     }
.LBB0_692:
	v_ashrrev_i32_e32 v47, 31, v4
	v_mov_b32_e32 v46, v4
	v_lshl_add_u64 v[46:47], v[46:47], 2, s[4:5]
	global_load_dword v5, v[46:47], off
	v_ashrrev_i32_e32 v47, 31, v0
	v_mov_b32_e32 v46, v0
	v_lshlrev_b64 v[46:47], 12, v[46:47]
	v_lshl_add_u64 v[16:17], v[2:3], 0, v[46:47]
	global_load_dwordx4 v[8:11], v[16:17], off
	global_load_dwordx4 v[12:15], v[16:17], off offset:16
	global_load_dword v50, v[16:17], off
	global_load_dword v51, v[16:17], off
.Lhn_a:
	v_add_u32_e32 v0, s92, v0
	v_add_u32_e32 v4, s2, v4
	v_cmp_lt_i32_e32 vcc, s8, v0
	s_or_b64 s[6:7], vcc, s[6:7]
	s_cbranch_vccnz .Lhn_a_last
	v_ashrrev_i32_e32 v47, 31, v4
	v_mov_b32_e32 v46, v4
	v_lshl_add_u64 v[46:47], v[46:47], 2, s[4:5]
	global_load_dword v34, v[46:47], off
	v_ashrrev_i32_e32 v47, 31, v0
	v_mov_b32_e32 v46, v0
	v_lshlrev_b64 v[46:47], 12, v[46:47]
	v_lshl_add_u64 v[44:45], v[2:3], 0, v[46:47]
	global_load_dwordx4 v[36:39], v[44:45], off
	global_load_dwordx4 v[40:43], v[44:45], off offset:16
	s_waitcnt vmcnt(5)
	s_branch .Lhn_a_go
.Lhn_a_last:
	s_waitcnt vmcnt(2)
.Lhn_a_go:
	v_fmamk_f32 v1, v5, 0x3b800000, v6
	v_mul_f32_e32 v5, 0x4b800000, v1
	v_cmp_gt_f32_e32 vcc, s3, v1
	v_lshlrev_b32_e32 v18, 16, v8
	v_and_b32_e32 v19, 0xffff0000, v8
	v_cndmask_b32_e32 v1, v1, v5, vcc
	v_rsq_f32_e32 v1, v1
	v_lshlrev_b32_e32 v28, 16, v9
	v_and_b32_e32 v29, 0xffff0000, v9
	v_lshlrev_b32_e32 v20, 16, v10
	v_mul_f32_e32 v5, 0x45800000, v1
	v_and_b32_e32 v21, 0xffff0000, v10
	v_lshlrev_b32_e32 v30, 16, v11
	v_and_b32_e32 v31, 0xffff0000, v11
	v_cndmask_b32_e32 v26, v1, v5, vcc
	v_lshlrev_b32_e32 v22, 16, v12
	v_and_b32_e32 v23, 0xffff0000, v12
	v_lshlrev_b32_e32 v32, 16, v13
	v_and_b32_e32 v33, 0xffff0000, v13
	v_lshlrev_b32_e32 v24, 16, v14
	v_and_b32_e32 v25, 0xffff0000, v14
	v_lshlrev_b32_e32 v48, 16, v15
	v_and_b32_e32 v49, 0xffff0000, v15
	v_pk_mul_f32 v[18:19], v[26:27], v[18:19] op_sel_hi:[0,1]
	v_pk_mul_f32 v[28:29], v[26:27], v[28:29] op_sel_hi:[0,1]
	v_pk_mul_f32 v[20:21], v[26:27], v[20:21] op_sel_hi:[0,1]
	v_pk_mul_f32 v[30:31], v[26:27], v[30:31] op_sel_hi:[0,1]
	v_pk_mul_f32 v[22:23], v[26:27], v[22:23] op_sel_hi:[0,1]
	v_pk_mul_f32 v[32:33], v[26:27], v[32:33] op_sel_hi:[0,1]
	v_pk_mul_f32 v[24:25], v[26:27], v[24:25] op_sel_hi:[0,1]
	v_pk_mul_f32 v[48:49], v[26:27], v[48:49] op_sel_hi:[0,1]
	v_cvt_pk_bf16_f32 v8, v18, v19
	v_cvt_pk_bf16_f32 v9, v28, v29
	v_cvt_pk_bf16_f32 v10, v20, v21
	v_cvt_pk_bf16_f32 v11, v30, v31
	v_cvt_pk_bf16_f32 v12, v22, v23
	v_cvt_pk_bf16_f32 v13, v32, v33
	v_cvt_pk_bf16_f32 v14, v24, v25
	v_cvt_pk_bf16_f32 v15, v48, v49
	global_store_dwordx4 v[16:17], v[8:11], off
	global_store_dwordx4 v[16:17], v[12:15], off offset:16
	s_andn2_b64 exec, exec, s[6:7]
	s_cbranch_execz .LBB0_693
.Lhn_b:
	v_add_u32_e32 v0, s92, v0
	v_add_u32_e32 v4, s2, v4
	v_cmp_lt_i32_e32 vcc, s8, v0
	s_or_b64 s[6:7], vcc, s[6:7]
	s_cbranch_vccnz .Lhn_b_last
	v_ashrrev_i32_e32 v47, 31, v4
	v_mov_b32_e32 v46, v4
	v_lshl_add_u64 v[46:47], v[46:47], 2, s[4:5]
	global_load_dword v5, v[46:47], off
	v_ashrrev_i32_e32 v47, 31, v0
	v_mov_b32_e32 v46, v0
	v_lshlrev_b64 v[46:47], 12, v[46:47]
	v_lshl_add_u64 v[16:17], v[2:3], 0, v[46:47]
	global_load_dwordx4 v[8:11], v[16:17], off
	global_load_dwordx4 v[12:15], v[16:17], off offset:16
	s_waitcnt vmcnt(5)
	s_branch .Lhn_b_go

; DI unsigned pk2(float a, float b) { f32x2 v = {a, b}; hbf2 r = __builtin_convertvector(v, hbf2); return __builtin_bit_cast(unsigned, r); }
; DI float bflo(unsigned u) { return __uint_as_float(u << 16); }
; DI float bfhi(unsigned u) { return __uint_as_float(u & 0xffff0000u); }
; DI int tid_fresh() { int t = threadIdx.x; asm volatile("" : "+v"(t)); return t; }
; DI void headnorm_phase(const Params& p) {
;     const int tid = tid_fresh(), lane = tid & 63, wid = tid >> 6;
;     bf16_t* OG = (bf16_t*)(p.ws + OFF_R3);
;     const float* HSS = (const float*)(p.ws + OFF_HSS);
;     for (int r = blockIdx.x * 8 + wid; r < MR + 16; r += gridDim.x * 8) {
;         const float sc = rsqrtf(HSS[r * 4 + (lane >> 4)] * (1.0f / 256.0f) + EPS);
;         bf16_t* op = OG + (size_t)r * 2048 + lane * 16;
; #pragma unroll
;         for (int i = 0; i < 2; ++i) {
;             const u32x4 v = *(const u32x4*)(op + i * 8);
;             u32x4 w;
;             w.x = pk2(bflo(v.x) * sc, bfhi(v.x) * sc); w.y = pk2(bflo(v.y) * sc, bfhi(v.y) * sc);
;             w.z = pk2(bflo(v.z) * sc, bfhi(v.z) * sc); w.w = pk2(bflo(v.w) * sc, bfhi(v.w) * sc);
;             *(u32x4*)(op + i * 8) = w;
;         }
;     }
.Lhn_b_go:
	v_fmamk_f32 v1, v34, 0x3b800000, v6
	v_mul_f32_e32 v34, 0x4b800000, v1
	v_cmp_gt_f32_e32 vcc, s3, v1
	v_lshlrev_b32_e32 v18, 16, v36
	v_and_b32_e32 v19, 0xffff0000, v36
	v_cndmask_b32_e32 v1, v1, v34, vcc
	v_rsq_f32_e32 v1, v1
	v_lshlrev_b32_e32 v28, 16, v37
	v_and_b32_e32 v29, 0xffff0000, v37
	v_lshlrev_b32_e32 v20, 16, v38
	v_mul_f32_e32 v34, 0x45800000, v1
	v_and_b32_e32 v21, 0xffff0000, v38
	v_lshlrev_b32_e32 v30, 16, v39
	v_and_b32_e32 v31, 0xffff0000, v39
	v_cndmask_b32_e32 v26, v1, v34, vcc
	v_lshlrev_b32_e32 v22, 16, v40
	v_and_b32_e32 v23, 0xffff0000, v40
	v_lshlrev_b32_e32 v32, 16, v41
	v_and_b32_e32 v33, 0xffff0000, v41
	v_lshlrev_b32_e32 v24, 16, v42
	v_and_b32_e32 v25, 0xffff0000, v42
	v_lshlrev_b32_e32 v48, 16, v43
	v_and_b32_e32 v49, 0xffff0000, v43
	v_pk_mul_f32 v[18:19], v[26:27], v[18:19] op_sel_hi:[0,1]
	v_pk_mul_f32 v[28:29], v[26:27], v[28:29] op_sel_hi:[0,1]
	v_pk_mul_f32 v[20:21], v[26:27], v[20:21] op_sel_hi:[0,1]
	v_pk_mul_f32 v[30:31], v[26:27], v[30:31] op_sel_hi:[0,1]
	v_pk_mul_f32 v[22:23], v[26:27], v[22:23] op_sel_hi:[0,1]
	v_pk_mul_f32 v[32:33], v[26:27], v[32:33] op_sel_hi:[0,1]
	v_pk_mul_f32 v[24:25], v[26:27], v[24:25] op_sel_hi:[0,1]
	v_pk_mul_f32 v[48:49], v[26:27], v[48:49] op_sel_hi:[0,1]
	v_cvt_pk_bf16_f32 v36, v18, v19
	v_cvt_pk_bf16_f32 v37, v28, v29
	v_cvt_pk_bf16_f32 v38, v20, v21
	v_cvt_pk_bf16_f32 v39, v30, v31
	v_cvt_pk_bf16_f32 v40, v22, v23
	v_cvt_pk_bf16_f32 v41, v32, v33
	v_cvt_pk_bf16_f32 v42, v24, v25
	v_cvt_pk_bf16_f32 v43, v48, v49
	global_store_dwordx4 v[44:45], v[36:39], off
	global_store_dwordx4 v[44:45], v[40:43], off offset:16
	s_andn2_b64 exec, exec, s[6:7]
	s_cbranch_execnz .Lhn_a

; DI int tid_fresh() { int t = threadIdx.x; asm volatile("" : "+v"(t)); return t; }
; DI void final_phase(const Params& p) {
;     const int tid = tid_fresh(), lane = tid & 63, wid = tid >> 6;
;     const float* h = (const float*)(p.ws + OFF_H);
;     const float* ss = (const float*)(p.ws + OFF_SS) + 3 * MP;
;     for (int r = blockIdx.x * 8 + wid; r < MR; r += gridDim.x * 8) {
;         const float rstd = rsqrtf(ss[r] * (1.0f / 1024.0f) + EPS);
; #pragma unroll
;         for (int i = 0; i < 4; ++i) {
;             const int c = i * 256 + lane * 4;
;             const f32x4 v = *(const f32x4*)(h + (size_t)r * 1024 + c);
;             const f32x4 g = *(const f32x4*)(p.norm_final + c);
;             *(f32x4*)(p.out + (size_t)r * 1024 + c) = v * rstd * g;
;         }
;     }
.LBB0_1611:
	s_or_b64 exec, exec, s[0:1]
	s_waitcnt lgkmcnt(0)
	s_barrier
	s_mov_b32 s0, 0x8000
	v_ashrrev_i32_e32 v0, 6, v178
	v_add_u32_e32 v0, s93, v0
	v_cmp_gt_i32_e32 vcc, s0, v0
	s_and_saveexec_b64 s[0:1], vcc
	s_cbranch_execz .LBB0_1614
	v_lshlrev_b32_e32 v1, 4, v178
	v_and_b32_e32 v6, 0x3f0, v1
	v_mov_b32_e32 v7, 0
	v_lshl_add_u64 v[2:3], s[64:65], 0, v[6:7]
	v_lshl_add_u64 v[4:5], s[66:67], 0, v[6:7]
	v_lshl_add_u64 v[6:7], s[52:53], 0, v[6:7]
	s_mov_b64 s[0:1], 0
	v_mov_b32_e32 v8, 0x358637bd
	s_mov_b32 s2, 0x800000
	s_movk_i32 s3, 0x7fff
	global_load_dwordx4 v[24:27], v[2:3], off
	global_load_dwordx4 v[28:31], v[2:3], off offset:1024
	global_load_dwordx4 v[32:35], v[2:3], off offset:2048
	global_load_dwordx4 v[36:39], v[2:3], off offset:3072
.LBB0_1613:
	v_ashrrev_i32_e32 v1, 31, v0
	v_lshl_add_u64 v[10:11], v[0:1], 2, s[6:7]
	global_load_dword v9, v[10:11], off
	v_lshlrev_b64 v[18:19], 12, v[0:1]
	v_lshl_add_u64 v[20:21], v[4:5], 0, v[18:19]
	global_load_dwordx4 v[40:43], v[20:21], off
	global_load_dwordx4 v[44:47], v[20:21], off offset:1024
	global_load_dwordx4 v[48:51], v[20:21], off offset:2048
	global_load_dwordx4 v[52:55], v[20:21], off offset:3072
	v_lshl_add_u64 v[18:19], v[6:7], 0, v[18:19]
	v_add_u32_e32 v0, s92, v0
	v_cmp_lt_i32_e32 vcc, s3, v0
	s_or_b64 s[0:1], vcc, s[0:1]
	s_waitcnt vmcnt(4)
	v_fmamk_f32 v1, v9, 0x3a800000, v8
	v_mul_f32_e32 v9, 0x4b800000, v1
	v_cmp_gt_f32_e32 vcc, s2, v1
	s_nop 1
	v_cndmask_b32_e32 v1, v1, v9, vcc
	v_rsq_f32_e32 v1, v1
	s_nop 0
	v_mul_f32_e32 v9, 0x45800000, v1
	v_cndmask_b32_e32 v22, v1, v9, vcc
	s_waitcnt vmcnt(3)
	v_pk_mul_f32 v[40:41], v[40:41], v[22:23] op_sel_hi:[1,0]
	v_pk_mul_f32 v[42:43], v[42:43], v[22:23] op_sel_hi:[1,0]
	v_pk_mul_f32 v[40:41], v[24:25], v[40:41]
	v_pk_mul_f32 v[42:43], v[26:27], v[42:43]
	global_store_dwordx4 v[18:19], v[40:43], off
	s_waitcnt vmcnt(3)
	v_pk_mul_f32 v[44:45], v[44:45], v[22:23] op_sel_hi:[1,0]
	v_pk_mul_f32 v[46:47], v[46:47], v[22:23] op_sel_hi:[1,0]
	v_pk_mul_f32 v[44:45], v[28:29], v[44:45]
	v_pk_mul_f32 v[46:47], v[30:31], v[46:47]
	global_store_dwordx4 v[18:19], v[44:47], off offset:1024
	s_waitcnt vmcnt(3)
	v_pk_mul_f32 v[48:49], v[48:49], v[22:23] op_sel_hi:[1,0]
	v_pk_mul_f32 v[50:51], v[50:51], v[22:23] op_sel_hi:[1,0]
	v_pk_mul_f32 v[48:49], v[32:33], v[48:49]
	v_pk_mul_f32 v[50:51], v[34:35], v[50:51]
	global_store_dwordx4 v[18:19], v[48:51], off offset:2048
	s_waitcnt vmcnt(3)
	v_pk_mul_f32 v[52:53], v[52:53], v[22:23] op_sel_hi:[1,0]
	v_pk_mul_f32 v[54:55], v[54:55], v[22:23] op_sel_hi:[1,0]
	v_pk_mul_f32 v[52:53], v[36:37], v[52:53]
	v_pk_mul_f32 v[54:55], v[38:39], v[54:55]
	global_store_dwordx4 v[18:19], v[52:55], off offset:3072
	s_andn2_b64 exec, exec, s[0:1]
	s_cbranch_execnz .LBB0_1613
